# v67 + umask OR-reduction via DPP row ops + readlanes (no LDS butterfly), rank loop LDS read software-pipelined
# speedup vs baseline: 1.0066x; 1.0012x over previous
.LBB0_671:
	s_or_b64 exec, exec, s[6:7]
	v_readlane_b32 s0, v249, 53
	s_waitcnt lgkmcnt(0)
	s_barrier
	v_lshl_add_u32 v16, v116, 8, s0
	v_lshl_add_u32 v6, v108, 2, v16
	ds_read_b128 v[2:5], v6
	ds_read_b128 v[6:9], v6 offset:16
	s_mov_b32 s16, 0
	v_mov_b32_e32 v17, 0
	v_mov_b32_e32 v18, 0
	v_mov_b32_e32 v19, 0
	v_mov_b32_e32 v20, 0
	v_mov_b32_e32 v21, 0
	v_mov_b32_e32 v22, 0
	v_mov_b32_e32 v23, 0
	v_mov_b32_e32 v24, 0
	ds_read_b128 v[204:207], v16
.LBB0_672:
	s_add_i32 s16, s16, 4
	v_add_u32_e32 v16, 16, v16
	s_cmp_le_u32 s16, s79
	s_waitcnt lgkmcnt(0)
	v_mov_b32_e32 v10, v204
	v_mov_b32_e32 v11, v205
	v_mov_b32_e32 v12, v206
	v_mov_b32_e32 v13, v207
	ds_read_b128 v[204:207], v16
	v_cmp_gt_u32_e64 s[0:1], v12, v3
	v_cmp_gt_u32_e64 s[6:7], v12, v5
	v_cmp_gt_u32_e64 s[10:11], v12, v7
	v_cndmask_b32_e64 v27, 0, 1, s[0:1]
	v_cmp_gt_u32_e64 s[0:1], v12, v2
	v_cndmask_b32_e64 v31, 0, 1, s[6:7]
	v_cmp_gt_u32_e64 s[6:7], v12, v4
	v_cndmask_b32_e64 v51, 0, 1, s[10:11]
	v_cmp_gt_u32_e64 s[10:11], v12, v6
	v_cmp_gt_u32_e32 vcc, v10, v2
	v_cndmask_b32_e64 v28, 0, 1, s[0:1]
	v_cmp_gt_u32_e64 s[0:1], v10, v4
	v_cndmask_b32_e64 v32, 0, 1, s[6:7]
	v_cmp_gt_u32_e64 s[6:7], v10, v6
	v_cndmask_b32_e64 v52, 0, 1, s[10:11]
	v_cmp_gt_u32_e64 s[10:11], v10, v8
	v_cmp_gt_u32_e64 s[14:15], v12, v9
	v_cndmask_b32_e64 v25, 0, 1, vcc
	v_cmp_gt_u32_e32 vcc, v10, v3
	v_cndmask_b32_e64 v29, 0, 1, s[0:1]
	v_cmp_gt_u32_e64 s[0:1], v10, v5
	v_cndmask_b32_e64 v33, 0, 1, s[6:7]
	v_cmp_gt_u32_e64 s[6:7], v10, v7
	v_cndmask_b32_e64 v53, 0, 1, s[10:11]
	v_cmp_gt_u32_e64 s[10:11], v10, v9
	v_cndmask_b32_e64 v54, 0, 1, s[14:15]
	v_cmp_gt_u32_e64 s[14:15], v12, v8
	v_cndmask_b32_e64 v26, 0, 1, vcc
	v_cmp_gt_u32_e32 vcc, v11, v2
	v_cndmask_b32_e64 v30, 0, 1, s[0:1]
	v_cmp_gt_u32_e64 s[0:1], v11, v4
	v_cmp_gt_u32_e64 s[4:5], v11, v5
	v_cndmask_b32_e64 v50, 0, 1, s[6:7]
	v_cmp_gt_u32_e64 s[6:7], v11, v6
	v_cmp_gt_u32_e64 s[8:9], v11, v7
	v_cndmask_b32_e64 v10, 0, 1, s[10:11]
	v_cmp_gt_u32_e64 s[10:11], v11, v8
	v_cmp_gt_u32_e64 s[12:13], v11, v9
	v_cndmask_b32_e64 v12, 0, 1, s[14:15]
	v_cmp_gt_u32_e64 s[14:15], v11, v3
	v_addc_co_u32_e32 v23, vcc, v23, v25, vcc
	s_nop 0
	v_addc_co_u32_e64 v11, s[14:15], v24, v26, s[14:15]
	v_addc_co_u32_e64 v22, s[4:5], v22, v30, s[4:5]
	v_addc_co_u32_e64 v21, s[0:1], v21, v29, s[0:1]
	v_addc_co_u32_e64 v20, s[8:9], v20, v50, s[8:9]
	v_addc_co_u32_e64 v19, s[6:7], v19, v33, s[6:7]
	v_addc_co_u32_e64 v10, s[12:13], v18, v10, s[12:13]
	v_addc_co_u32_e64 v17, s[10:11], v17, v53, s[10:11]
	v_cmp_gt_u32_e32 vcc, v13, v3
	v_cmp_gt_u32_e64 s[0:1], v13, v5
	v_cmp_gt_u32_e64 s[4:5], v13, v4
	v_cmp_gt_u32_e64 s[6:7], v13, v7
	v_cmp_gt_u32_e64 s[8:9], v13, v6
	v_cmp_gt_u32_e64 s[10:11], v13, v9
	v_cmp_gt_u32_e64 s[12:13], v13, v8
	v_cmp_gt_u32_e64 s[14:15], v13, v2
	v_addc_co_u32_e32 v24, vcc, v11, v27, vcc
	s_nop 0
	v_addc_co_u32_e64 v23, s[14:15], v23, v28, s[14:15]
	v_addc_co_u32_e64 v21, vcc, v21, v32, s[4:5]
	v_addc_co_u32_e64 v22, vcc, v22, v31, s[0:1]
	v_addc_co_u32_e64 v19, vcc, v19, v52, s[8:9]
	v_addc_co_u32_e64 v20, vcc, v20, v51, s[6:7]
	v_addc_co_u32_e64 v17, vcc, v17, v12, s[12:13]
	v_addc_co_u32_e64 v18, vcc, v10, v54, s[10:11]
	s_cbranch_scc1 .LBB0_672
	v_cmp_gt_i32_e32 vcc, 16, v23
	v_readlane_b32 s0, v249, 55
	s_nop 0
	v_cndmask_b32_e64 v2, 0, 1, vcc
	v_cmp_gt_i32_e32 vcc, 16, v24
	s_nop 1
	v_cndmask_b32_e64 v3, 0, 2, vcc
	v_cmp_gt_i32_e32 vcc, 16, v21
	v_or_b32_e32 v2, v3, v2
	s_nop 0
	v_cndmask_b32_e64 v3, 0, 4, vcc
	v_cmp_gt_i32_e32 vcc, 16, v22
	s_nop 1
	v_cndmask_b32_e64 v4, 0, 8, vcc
	v_cmp_gt_i32_e32 vcc, 16, v19
	v_bitop3_b16 v2, v2, v4, v3 bitop3:0xfe
	s_nop 0
	v_cndmask_b32_e64 v3, 0, 16, vcc
	v_cmp_gt_i32_e32 vcc, 16, v20
	s_nop 1
	v_cndmask_b32_e64 v4, 0, 32, vcc
	v_cmp_gt_i32_e32 vcc, 16, v17
	v_bitop3_b16 v2, v2, v4, v3 bitop3:0xfe
	s_nop 0
	v_cndmask_b32_e64 v3, 0, 64, vcc
	v_cmp_gt_i32_e32 vcc, 16, v18
	s_nop 1
	v_cndmask_b32_e32 v4, 0, v162, vcc
	v_bitop3_b16 v2, v2, v4, v3 bitop3:0xfe
	v_add_u32_e32 v3, s0, v106
	ds_write_b8 v3, v2
	v_lshl_add_u32 v2, v107, 3, s0
	s_waitcnt lgkmcnt(0)
	s_barrier
	ds_read_b64 v[2:3], v2
	v_lshl_add_u32 v4, v169, 3, s0
	ds_read_b64 v[4:5], v4
	s_waitcnt lgkmcnt(0)
	v_and_b32_e32 v149, s93, v5
	v_and_b32_e32 v148, s92, v4
	s_nop 1
	v_or_b32_dpp v2, v2, v2 quad_perm:[1,0,3,2] row_mask:0xf bank_mask:0xf
	v_or_b32_dpp v3, v3, v3 quad_perm:[1,0,3,2] row_mask:0xf bank_mask:0xf
	s_nop 1
	v_or_b32_dpp v2, v2, v2 quad_perm:[2,3,0,1] row_mask:0xf bank_mask:0xf
	v_or_b32_dpp v3, v3, v3 quad_perm:[2,3,0,1] row_mask:0xf bank_mask:0xf
	s_nop 1
	v_or_b32_dpp v2, v2, v2 row_half_mirror row_mask:0xf bank_mask:0xf
	v_or_b32_dpp v3, v3, v3 row_half_mirror row_mask:0xf bank_mask:0xf
	s_nop 1
	v_or_b32_dpp v2, v2, v2 row_mirror row_mask:0xf bank_mask:0xf
	v_or_b32_dpp v3, v3, v3 row_mirror row_mask:0xf bank_mask:0xf
	s_nop 1
	v_readlane_b32 s0, v2, 0
	v_readlane_b32 s1, v3, 0
	v_readlane_b32 s10, v2, 16
	v_readlane_b32 s11, v3, 16
	s_or_b64 s[0:1], s[0:1], s[10:11]
	v_readlane_b32 s10, v2, 32
	v_readlane_b32 s11, v3, 32
	s_or_b64 s[0:1], s[0:1], s[10:11]
	v_readlane_b32 s10, v2, 48
	v_readlane_b32 s11, v3, 48
	s_or_b64 s[0:1], s[0:1], s[10:11]
	s_and_b64 s[4:5], s[0:1], s[92:93]
